# speedup vs baseline: 1.0095x; 1.0095x over previous
; #define PG8_STAGE(bufoff, gbase, voff) do { _Pragma("unroll") for (int _i = 0; _i < 2; ++_i) \
;         __builtin_amdgcn_global_load_lds((const unsigned*)((const char*)(gbase) + (voff)[_i]), (PG8_LAS unsigned*)(lds + (bufoff) + ldsw + _i * 8192), 16, 0, 0); } while (0)
; #define PG8_LDA(dst, b, h) do { _Pragma("unroll") for (int m = 0; m < 4; ++m) _Pragma("unroll") for (int k = 0; k < 2; ++k) dst[m][k] = *(const PG8_LAS bf16x8*)(lds + PG8_SA(b, h) + aoff + m * 2048 + k * 1024); } while (0)
; #define PG8_LDB(dst, b, h) do { _Pragma("unroll") for (int n = 0; n < 2; ++n) _Pragma("unroll") for (int k = 0; k < 2; ++k) dst[n][k] = *(const PG8_LAS bf16x8*)(lds + PG8_SB(b, h) + boff + n * 2048 + k * 1024); } while (0)
; #define PG8_MMA(ai, bj, At, Bt) do { __builtin_amdgcn_s_setprio(1); _Pragma("unroll") for (int m = 0; m < 4; ++m) _Pragma("unroll") for (int n = 0; n < 2; ++n) _Pragma("unroll") for (int k = 0; k < 2; ++k) \
;         acc[ai][bj][m][n] = __builtin_amdgcn_mfma_f32_16x16x32_bf16(Bt[n][k], At[m][k], acc[ai][bj][m][n], 0, 0, 0); __builtin_amdgcn_s_setprio(0); } while (0)
; #define PG8_WAIT_V(n) asm volatile("s_waitcnt vmcnt(" #n ")" ::: "memory")
; #define PG8_WAIT_L(n) asm volatile("s_waitcnt lgkmcnt(" #n ")" ::: "memory")
; #define PG8_BAR __builtin_amdgcn_s_barrier()
; #define PG8_SCHED __builtin_amdgcn_sched_barrier(0)
; template <class Epi, class Sched, bool ALIGN_EPI = false, bool SP2 = false>
; __device__ __forceinline__ void gemm_phase(PG8_LAS unsigned char* lds, const Gemm g, const Sched& S, const Epi& E) {
;     ...
;         const long nks = has_next ? (((ui + 1) & 1) ? -kstep : kstep) : ks;
;         const long nk0 = (long)(nxt.kt0 + (nks < 0 ? nxt.nkt - 1 : 0)) * kstep;
;         const char* nA = has_next ? (const char*)g.A + (size_t)nxt.pm * tstep + nk0 : cA; const char* nB = has_next ? (const char*)g.Bt + (size_t)nxt.pn * tstep + nk0 : cB;
;     ...
;             PG8_LDB(B0, 0, 0); PG8_LDB(B1, 0, 1); PG8_SCHED; PG8_LDA(At, 0, 0); PG8_STAGE(PG8_SA(1, 1), a1 + hstep, voffA);
;             PG8_WAIT_V(8); PG8_WAIT_L(0); PG8_BAR; PG8_MMA(0, 0, At, B0); PG8_MMA(0, 1, At, B1); PG8_BAR; PG8_SCHED;
;             PG8_LDA(At, 0, 1); PG8_STAGE(PG8_SB(0, 0), b2, voffB); PG8_STAGE(PG8_SB(0, 1), b2 + hstep, voffB); PG8_STAGE(PG8_SA(0, 0), a2, voffA);
;             PG8_WAIT_V(8); PG8_WAIT_L(0); PG8_BAR; PG8_MMA(1, 0, At, B0); PG8_MMA(1, 1, At, B1); PG8_BAR; PG8_SCHED;
.LBB0_354:
	s_add_i32 s88, s13, -2
	s_lshl_b64 s[48:49], s[44:45], 1
	s_add_u32 s87, s50, s48
	v_lshl_add_u64 v[2:3], s[56:57], 0, v[136:137]
	s_addc_u32 s33, s51, s49
	v_lshl_add_u64 v[140:141], v[2:3], 0, s[44:45]
	v_lshl_add_u64 v[2:3], s[56:57], 0, v[138:139]
	s_add_u32 s18, s56, s48
	v_lshl_add_u64 v[142:143], v[2:3], 0, s[44:45]
	s_addc_u32 s19, s57, s49
	s_mov_b32 s80, 0
	s_mov_b64 s[50:51], 0
	s_branch .LBB0_356
.LBB0_355:
	s_add_i32 s80, s80, 2
	s_add_u32 s82, s62, s60
	s_addc_u32 s83, s63, s61
	ds_read_b128 v[148:151], v242
	ds_read_b128 v[152:155], v242 offset:1024
	ds_read_b128 v[156:159], v242 offset:2048
	ds_read_b128 v[160:163], v242 offset:3072
	ds_read_b128 v[164:167], v242 offset:16384
	ds_read_b128 v[168:171], v242 offset:17408
	ds_read_b128 v[172:175], v242 offset:18432
	ds_read_b128 v[176:179], v242 offset:19456
	v_lshl_add_u64 v[232:233], v[140:141], 0, s[50:51]
	s_add_i32 m0, s98, 0xc000
	ds_read_b128 v[182:185], v147
	ds_read_b128 v[186:189], v147 offset:1024
	ds_read_b128 v[208:211], v147 offset:2048
	ds_read_b128 v[212:215], v147 offset:3072
	ds_read_b128 v[216:219], v147 offset:4096
	ds_read_b128 v[220:223], v147 offset:5120
	ds_read_b128 v[224:227], v147 offset:6144
	ds_read_b128 v[228:231], v147 offset:7168
	global_load_lds_dwordx4 v[232:233], off
	v_lshl_add_u64 v[232:233], v[142:143], 0, s[50:51]
	s_add_i32 m0, s98, 0xe000
	s_nop 0
	global_load_lds_dwordx4 v[232:233], off
	s_waitcnt vmcnt(8)
	s_waitcnt lgkmcnt(0)
	s_barrier
	s_setprio 1
	v_mfma_f32_16x16x32_bf16 v[126:129], v[148:151], v[182:185], 0
	v_mfma_f32_16x16x32_bf16 v[122:125], v[156:159], v[182:185], 0
	v_mfma_f32_16x16x32_bf16 v[118:121], v[148:151], v[208:211], 0
	v_mfma_f32_16x16x32_bf16 v[110:113], v[156:159], v[208:211], 0
	v_mfma_f32_16x16x32_bf16 v[102:105], v[148:151], v[216:219], 0
	v_mfma_f32_16x16x32_bf16 v[94:97], v[156:159], v[216:219], 0
	v_mfma_f32_16x16x32_bf16 v[86:89], v[148:151], v[224:227], 0
	v_mfma_f32_16x16x32_bf16 v[78:81], v[156:159], v[224:227], 0
	v_mfma_f32_16x16x32_bf16 v[126:129], v[152:155], v[186:189], v[126:129]
	v_mfma_f32_16x16x32_bf16 v[122:125], v[160:163], v[186:189], v[122:125]
	v_mfma_f32_16x16x32_bf16 v[118:121], v[152:155], v[212:215], v[118:121]
	v_mfma_f32_16x16x32_bf16 v[110:113], v[160:163], v[212:215], v[110:113]
	v_mfma_f32_16x16x32_bf16 v[102:105], v[152:155], v[220:223], v[102:105]
	v_mfma_f32_16x16x32_bf16 v[94:97], v[160:163], v[220:223], v[94:97]
	v_mfma_f32_16x16x32_bf16 v[86:89], v[152:155], v[228:231], v[86:89]
	v_mfma_f32_16x16x32_bf16 v[78:81], v[160:163], v[228:231], v[78:81]
	v_mfma_f32_16x16x32_bf16 v[114:117], v[164:167], v[182:185], 0
	v_mfma_f32_16x16x32_bf16 v[106:109], v[172:175], v[182:185], 0
	v_mfma_f32_16x16x32_bf16 v[98:101], v[164:167], v[208:211], 0
	v_mfma_f32_16x16x32_bf16 v[90:93], v[172:175], v[208:211], 0
	v_mfma_f32_16x16x32_bf16 v[82:85], v[164:167], v[216:219], 0
	v_mfma_f32_16x16x32_bf16 v[74:77], v[172:175], v[216:219], 0
	v_mfma_f32_16x16x32_bf16 v[70:73], v[164:167], v[224:227], 0
	v_mfma_f32_16x16x32_bf16 v[66:69], v[172:175], v[224:227], 0
	v_mfma_f32_16x16x32_bf16 v[114:117], v[168:171], v[186:189], v[114:117]
	v_mfma_f32_16x16x32_bf16 v[106:109], v[176:179], v[186:189], v[106:109]
	v_mfma_f32_16x16x32_bf16 v[98:101], v[168:171], v[212:215], v[98:101]
	v_mfma_f32_16x16x32_bf16 v[90:93], v[176:179], v[212:215], v[90:93]
	v_mfma_f32_16x16x32_bf16 v[82:85], v[168:171], v[220:223], v[82:85]
	v_mfma_f32_16x16x32_bf16 v[74:77], v[176:179], v[220:223], v[74:77]
	v_mfma_f32_16x16x32_bf16 v[70:73], v[168:171], v[228:231], v[70:73]
	v_mfma_f32_16x16x32_bf16 v[66:69], v[176:179], v[228:231], v[66:69]
	s_setprio 0
	s_barrier
	s_add_i32 m0, s97, 0x10000
	ds_read_b128 v[182:185], v147 offset:16384
	ds_read_b128 v[186:189], v147 offset:17408
	ds_read_b128 v[208:211], v147 offset:18432
	ds_read_b128 v[212:215], v147 offset:19456
	ds_read_b128 v[216:219], v147 offset:20480
	ds_read_b128 v[220:223], v147 offset:21504
	ds_read_b128 v[224:227], v147 offset:22528
	ds_read_b128 v[228:231], v147 offset:23552
	global_load_lds_dwordx4 v0, s[56:57]
	s_add_i32 m0, s97, 0x12000
	s_add_u32 s38, s56, s16
	s_addc_u32 s39, s57, 0
	global_load_lds_dwordx4 v134, s[56:57]
	s_add_i32 m0, s97, 0x14000
	s_nop 0
	global_load_lds_dwordx4 v0, s[38:39]
	s_add_i32 m0, s97, 0x16000
	s_nop 0
	global_load_lds_dwordx4 v134, s[38:39]
	s_mov_b32 m0, s98
	s_nop 0
	global_load_lds_dwordx4 v130, s[62:63]
	s_mov_b32 m0, s99
	s_nop 0
	global_load_lds_dwordx4 v132, s[62:63]
	s_waitcnt vmcnt(8)
	s_waitcnt lgkmcnt(0)
	s_barrier
; #define PG8_STAGE(bufoff, gbase, voff) do { _Pragma("unroll") for (int _i = 0; _i < 2; ++_i) \
;         __builtin_amdgcn_global_load_lds((const unsigned*)((const char*)(gbase) + (voff)[_i]), (PG8_LAS unsigned*)(lds + (bufoff) + ldsw + _i * 8192), 16, 0, 0); } while (0)
; #define PG8_LDA(dst, b, h) do { _Pragma("unroll") for (int m = 0; m < 4; ++m) _Pragma("unroll") for (int k = 0; k < 2; ++k) dst[m][k] = *(const PG8_LAS bf16x8*)(lds + PG8_SA(b, h) + aoff + m * 2048 + k * 1024); } while (0)
; #define PG8_LDB(dst, b, h) do { _Pragma("unroll") for (int n = 0; n < 2; ++n) _Pragma("unroll") for (int k = 0; k < 2; ++k) dst[n][k] = *(const PG8_LAS bf16x8*)(lds + PG8_SB(b, h) + boff + n * 2048 + k * 1024); } while (0)
; #define PG8_MMA(ai, bj, At, Bt) do { __builtin_amdgcn_s_setprio(1); _Pragma("unroll") for (int m = 0; m < 4; ++m) _Pragma("unroll") for (int n = 0; n < 2; ++n) _Pragma("unroll") for (int k = 0; k < 2; ++k) \
;         acc[ai][bj][m][n] = __builtin_amdgcn_mfma_f32_16x16x32_bf16(Bt[n][k], At[m][k], acc[ai][bj][m][n], 0, 0, 0); __builtin_amdgcn_s_setprio(0); } while (0)
; #define PG8_WAIT_V(n) asm volatile("s_waitcnt vmcnt(" #n ")" ::: "memory")
; #define PG8_WAIT_L(n) asm volatile("s_waitcnt lgkmcnt(" #n ")" ::: "memory")
; #define PG8_BAR __builtin_amdgcn_s_barrier()
; #define PG8_SCHED __builtin_amdgcn_sched_barrier(0)
; template <class Epi, class Sched, bool ALIGN_EPI = false, bool SP2 = false>
; __device__ __forceinline__ void gemm_phase(PG8_LAS unsigned char* lds, const Gemm g, const Sched& S, const Epi& E) {
;     ...
;             PG8_WAIT_V(8); PG8_WAIT_L(0); PG8_BAR; PG8_MMA(1, 0, At, B0); PG8_MMA(1, 1, At, B1); PG8_BAR; PG8_SCHED;
;             PG8_LDB(B0, 1, 0); PG8_LDB(B1, 1, 1); PG8_SCHED; PG8_LDA(At, 1, 0); PG8_STAGE(PG8_SA(0, 1), a2 + hstep, voffA);
;             PG8_WAIT_V(8); PG8_WAIT_L(0); PG8_BAR; PG8_MMA(0, 0, At, B0); PG8_MMA(0, 1, At, B1); PG8_BAR; PG8_SCHED;
;             PG8_LDA(At, 1, 1); PG8_STAGE(PG8_SB(1, 0), b3, voffB); PG8_STAGE(PG8_SB(1, 1), b3 + hstep, voffB); PG8_STAGE(PG8_SA(1, 0), a3, voffA);
;             PG8_WAIT_V(8); PG8_WAIT_L(0); PG8_BAR; PG8_MMA(1, 0, At, B0); PG8_MMA(1, 1, At, B1); PG8_BAR; PG8_SCHED;
	s_setprio 1
	v_mfma_f32_16x16x32_bf16 v[62:65], v[148:151], v[182:185], 0
	v_mfma_f32_16x16x32_bf16 v[58:61], v[156:159], v[182:185], 0
	v_mfma_f32_16x16x32_bf16 v[54:57], v[148:151], v[208:211], 0
	v_mfma_f32_16x16x32_bf16 v[46:49], v[156:159], v[208:211], 0
	v_mfma_f32_16x16x32_bf16 v[38:41], v[148:151], v[216:219], 0
	v_mfma_f32_16x16x32_bf16 v[30:33], v[156:159], v[216:219], 0
	v_mfma_f32_16x16x32_bf16 v[22:25], v[148:151], v[224:227], 0
	v_mfma_f32_16x16x32_bf16 v[14:17], v[156:159], v[224:227], 0
	v_mfma_f32_16x16x32_bf16 v[62:65], v[152:155], v[186:189], v[62:65]
	v_mfma_f32_16x16x32_bf16 v[58:61], v[160:163], v[186:189], v[58:61]
	v_mfma_f32_16x16x32_bf16 v[54:57], v[152:155], v[212:215], v[54:57]
	v_mfma_f32_16x16x32_bf16 v[46:49], v[160:163], v[212:215], v[46:49]
	v_mfma_f32_16x16x32_bf16 v[38:41], v[152:155], v[220:223], v[38:41]
	v_mfma_f32_16x16x32_bf16 v[30:33], v[160:163], v[220:223], v[30:33]
	v_mfma_f32_16x16x32_bf16 v[22:25], v[152:155], v[228:231], v[22:25]
	v_mfma_f32_16x16x32_bf16 v[14:17], v[160:163], v[228:231], v[14:17]
	v_mfma_f32_16x16x32_bf16 v[50:53], v[164:167], v[182:185], 0
	v_mfma_f32_16x16x32_bf16 v[42:45], v[172:175], v[182:185], 0
	v_mfma_f32_16x16x32_bf16 v[34:37], v[164:167], v[208:211], 0
	v_mfma_f32_16x16x32_bf16 v[26:29], v[172:175], v[208:211], 0
	v_mfma_f32_16x16x32_bf16 v[18:21], v[164:167], v[216:219], 0
	v_mfma_f32_16x16x32_bf16 v[10:13], v[172:175], v[216:219], 0
	v_mfma_f32_16x16x32_bf16 v[6:9], v[164:167], v[224:227], 0
	v_mfma_f32_16x16x32_bf16 v[2:5], v[172:175], v[224:227], 0
	v_mfma_f32_16x16x32_bf16 v[50:53], v[168:171], v[186:189], v[50:53]
	v_mfma_f32_16x16x32_bf16 v[42:45], v[176:179], v[186:189], v[42:45]
	v_mfma_f32_16x16x32_bf16 v[34:37], v[168:171], v[212:215], v[34:37]
	v_mfma_f32_16x16x32_bf16 v[26:29], v[176:179], v[212:215], v[26:29]
	v_mfma_f32_16x16x32_bf16 v[18:21], v[168:171], v[220:223], v[18:21]
	v_mfma_f32_16x16x32_bf16 v[10:13], v[176:179], v[220:223], v[10:13]
	v_mfma_f32_16x16x32_bf16 v[6:9], v[168:171], v[228:231], v[6:9]
	v_mfma_f32_16x16x32_bf16 v[2:5], v[176:179], v[228:231], v[2:5]
	s_setprio 0
	s_barrier
	ds_read_b128 v[148:151], v242 offset:32768
	ds_read_b128 v[152:155], v242 offset:33792
	ds_read_b128 v[156:159], v242 offset:34816
	ds_read_b128 v[160:163], v242 offset:35840
	ds_read_b128 v[164:167], v242 offset:49152
	ds_read_b128 v[168:171], v242 offset:50176
	ds_read_b128 v[172:175], v242 offset:51200
	ds_read_b128 v[176:179], v242 offset:52224
	s_add_u32 s38, s62, s16
	s_addc_u32 s39, s63, 0
	s_mov_b32 m0, s68
	ds_read_b128 v[182:185], v147 offset:32768
	ds_read_b128 v[186:189], v147 offset:33792
	ds_read_b128 v[208:211], v147 offset:34816
	ds_read_b128 v[212:215], v147 offset:35840
	ds_read_b128 v[216:219], v147 offset:36864
	ds_read_b128 v[220:223], v147 offset:37888
	ds_read_b128 v[224:227], v147 offset:38912
	ds_read_b128 v[228:231], v147 offset:39936
	global_load_lds_dwordx4 v130, s[38:39]
	s_mov_b32 m0, s64
	s_nop 0
	global_load_lds_dwordx4 v132, s[38:39]
	s_waitcnt vmcnt(8)
	s_waitcnt lgkmcnt(0)
	s_barrier
	s_setprio 1
	v_mfma_f32_16x16x32_bf16 v[126:129], v[148:151], v[182:185], v[126:129]
	v_mfma_f32_16x16x32_bf16 v[122:125], v[156:159], v[182:185], v[122:125]
	v_mfma_f32_16x16x32_bf16 v[118:121], v[148:151], v[208:211], v[118:121]
	v_mfma_f32_16x16x32_bf16 v[110:113], v[156:159], v[208:211], v[110:113]
	v_mfma_f32_16x16x32_bf16 v[102:105], v[148:151], v[216:219], v[102:105]
	v_mfma_f32_16x16x32_bf16 v[94:97], v[156:159], v[216:219], v[94:97]
	v_mfma_f32_16x16x32_bf16 v[86:89], v[148:151], v[224:227], v[86:89]
	v_mfma_f32_16x16x32_bf16 v[78:81], v[156:159], v[224:227], v[78:81]
	v_mfma_f32_16x16x32_bf16 v[126:129], v[152:155], v[186:189], v[126:129]
	v_mfma_f32_16x16x32_bf16 v[122:125], v[160:163], v[186:189], v[122:125]
	v_mfma_f32_16x16x32_bf16 v[118:121], v[152:155], v[212:215], v[118:121]
	v_mfma_f32_16x16x32_bf16 v[110:113], v[160:163], v[212:215], v[110:113]
	v_mfma_f32_16x16x32_bf16 v[102:105], v[152:155], v[220:223], v[102:105]
	v_mfma_f32_16x16x32_bf16 v[94:97], v[160:163], v[220:223], v[94:97]
	v_mfma_f32_16x16x32_bf16 v[86:89], v[152:155], v[228:231], v[86:89]
	v_mfma_f32_16x16x32_bf16 v[78:81], v[160:163], v[228:231], v[78:81]
	v_mfma_f32_16x16x32_bf16 v[114:117], v[164:167], v[182:185], v[114:117]
	v_mfma_f32_16x16x32_bf16 v[106:109], v[172:175], v[182:185], v[106:109]
	v_mfma_f32_16x16x32_bf16 v[98:101], v[164:167], v[208:211], v[98:101]
	v_mfma_f32_16x16x32_bf16 v[90:93], v[172:175], v[208:211], v[90:93]
	v_mfma_f32_16x16x32_bf16 v[82:85], v[164:167], v[216:219], v[82:85]
	v_mfma_f32_16x16x32_bf16 v[74:77], v[172:175], v[216:219], v[74:77]
	v_mfma_f32_16x16x32_bf16 v[70:73], v[164:167], v[224:227], v[70:73]
	v_mfma_f32_16x16x32_bf16 v[66:69], v[172:175], v[224:227], v[66:69]
	v_mfma_f32_16x16x32_bf16 v[114:117], v[168:171], v[186:189], v[114:117]
	v_mfma_f32_16x16x32_bf16 v[106:109], v[176:179], v[186:189], v[106:109]
	v_mfma_f32_16x16x32_bf16 v[98:101], v[168:171], v[212:215], v[98:101]
	v_mfma_f32_16x16x32_bf16 v[90:93], v[176:179], v[212:215], v[90:93]
	v_mfma_f32_16x16x32_bf16 v[82:85], v[168:171], v[220:223], v[82:85]
	v_mfma_f32_16x16x32_bf16 v[74:77], v[176:179], v[220:223], v[74:77]
	v_mfma_f32_16x16x32_bf16 v[70:73], v[168:171], v[228:231], v[70:73]
	v_mfma_f32_16x16x32_bf16 v[66:69], v[176:179], v[228:231], v[66:69]
	s_setprio 0
	s_barrier
	s_add_u32 s38, s56, s60
	s_addc_u32 s39, s57, s61
	s_add_i32 m0, s97, 0x18000
	ds_read_b128 v[182:185], v147 offset:49152
	ds_read_b128 v[186:189], v147 offset:50176
	ds_read_b128 v[208:211], v147 offset:51200
	ds_read_b128 v[212:215], v147 offset:52224
	ds_read_b128 v[216:219], v147 offset:53248
	ds_read_b128 v[220:223], v147 offset:54272
	ds_read_b128 v[224:227], v147 offset:55296
	ds_read_b128 v[228:231], v147 offset:56320
	global_load_lds_dwordx4 v0, s[38:39]
	s_add_i32 m0, s97, 0x1a000
	s_nop 0
	global_load_lds_dwordx4 v134, s[38:39]
	s_add_u32 s38, s38, s16
	s_addc_u32 s39, s39, 0
	s_add_i32 m0, s97, 0x1c000
	global_load_lds_dwordx4 v0, s[38:39]
	s_add_i32 m0, s97, 0x1e000
	s_nop 0
	global_load_lds_dwordx4 v134, s[38:39]
	s_mov_b32 m0, s72
	s_nop 0
	global_load_lds_dwordx4 v130, s[82:83]
	s_mov_b32 m0, s73
	s_nop 0
	global_load_lds_dwordx4 v132, s[82:83]
	s_add_u32 s50, s50, s48
	s_addc_u32 s51, s51, s49
	s_cmp_ge_u32 s80, s13
	s_cselect_b64 vcc, -1, 0
	s_cbranch_scc1 .Lgemm_ctl_done_p
	s_cmp_eq_u32 s88, s80
	s_cbranch_scc1 .Lgemm_ctl_last_p
	s_add_u32 s62, s18, s50
	s_addc_u32 s63, s19, s51
	s_add_u32 s56, s87, s50
	s_addc_u32 s57, s33, s51
	s_mov_b64 s[60:61], s[44:45]
	s_branch .Lgemm_ctl_join_p

; #define PG8_STAGE(bufoff, gbase, voff) do { _Pragma("unroll") for (int _i = 0; _i < 2; ++_i) \
;         __builtin_amdgcn_global_load_lds((const unsigned*)((const char*)(gbase) + (voff)[_i]), (PG8_LAS unsigned*)(lds + (bufoff) + ldsw + _i * 8192), 16, 0, 0); } while (0)
; #define PG8_LDA(dst, b, h) do { _Pragma("unroll") for (int m = 0; m < 4; ++m) _Pragma("unroll") for (int k = 0; k < 2; ++k) dst[m][k] = *(const PG8_LAS bf16x8*)(lds + PG8_SA(b, h) + aoff + m * 2048 + k * 1024); } while (0)
; #define PG8_LDB(dst, b, h) do { _Pragma("unroll") for (int n = 0; n < 2; ++n) _Pragma("unroll") for (int k = 0; k < 2; ++k) dst[n][k] = *(const PG8_LAS bf16x8*)(lds + PG8_SB(b, h) + boff + n * 2048 + k * 1024); } while (0)
; #define PG8_MMA(ai, bj, At, Bt) do { __builtin_amdgcn_s_setprio(1); _Pragma("unroll") for (int m = 0; m < 4; ++m) _Pragma("unroll") for (int n = 0; n < 2; ++n) _Pragma("unroll") for (int k = 0; k < 2; ++k) \
;         acc[ai][bj][m][n] = __builtin_amdgcn_mfma_f32_16x16x32_bf16(Bt[n][k], At[m][k], acc[ai][bj][m][n], 0, 0, 0); __builtin_amdgcn_s_setprio(0); } while (0)
; #define PG8_WAIT_V(n) asm volatile("s_waitcnt vmcnt(" #n ")" ::: "memory")
; #define PG8_WAIT_L(n) asm volatile("s_waitcnt lgkmcnt(" #n ")" ::: "memory")
; #define PG8_BAR __builtin_amdgcn_s_barrier()
; #define PG8_SCHED __builtin_amdgcn_sched_barrier(0)
; template <class Epi, class Sched, bool ALIGN_EPI = false, bool SP2 = false>
; __device__ __forceinline__ void gemm_phase(PG8_LAS unsigned char* lds, const Gemm g, const Sched& S, const Epi& E) {
;     ...
;             PG8_LDB(B0, 0, 0); PG8_LDB(B1, 0, 1); PG8_SCHED; PG8_LDA(At, 0, 0); PG8_STAGE(PG8_SA(1, 1), a1 + hstep, voffA);
;             PG8_WAIT_V(8); PG8_WAIT_L(0); PG8_BAR; PG8_MMA(0, 0, At, B0); PG8_MMA(0, 1, At, B1); PG8_BAR; PG8_SCHED;
;     ...
;             PG8_WAIT_V(8); PG8_WAIT_L(0); PG8_BAR; PG8_MMA(1, 0, At, B0); PG8_MMA(1, 1, At, B1); PG8_BAR; PG8_SCHED;
.Lgemm_ctl_done_p:
	s_waitcnt vmcnt(8)
	s_waitcnt lgkmcnt(0)
	s_barrier
	s_setprio 1
	v_mfma_f32_16x16x32_bf16 v[62:65], v[148:151], v[182:185], v[62:65]
	v_mfma_f32_16x16x32_bf16 v[58:61], v[156:159], v[182:185], v[58:61]
	v_mfma_f32_16x16x32_bf16 v[54:57], v[148:151], v[208:211], v[54:57]
	v_mfma_f32_16x16x32_bf16 v[46:49], v[156:159], v[208:211], v[46:49]
	v_mfma_f32_16x16x32_bf16 v[38:41], v[148:151], v[216:219], v[38:41]
	v_mfma_f32_16x16x32_bf16 v[30:33], v[156:159], v[216:219], v[30:33]
	v_mfma_f32_16x16x32_bf16 v[22:25], v[148:151], v[224:227], v[22:25]
	v_mfma_f32_16x16x32_bf16 v[14:17], v[156:159], v[224:227], v[14:17]
	v_mfma_f32_16x16x32_bf16 v[62:65], v[152:155], v[186:189], v[62:65]
	v_mfma_f32_16x16x32_bf16 v[58:61], v[160:163], v[186:189], v[58:61]
	v_mfma_f32_16x16x32_bf16 v[54:57], v[152:155], v[212:215], v[54:57]
	v_mfma_f32_16x16x32_bf16 v[46:49], v[160:163], v[212:215], v[46:49]
	v_mfma_f32_16x16x32_bf16 v[38:41], v[152:155], v[220:223], v[38:41]
	v_mfma_f32_16x16x32_bf16 v[30:33], v[160:163], v[220:223], v[30:33]
	v_mfma_f32_16x16x32_bf16 v[22:25], v[152:155], v[228:231], v[22:25]
	v_mfma_f32_16x16x32_bf16 v[14:17], v[160:163], v[228:231], v[14:17]
	v_mfma_f32_16x16x32_bf16 v[50:53], v[164:167], v[182:185], v[50:53]
	v_mfma_f32_16x16x32_bf16 v[42:45], v[172:175], v[182:185], v[42:45]
	v_mfma_f32_16x16x32_bf16 v[34:37], v[164:167], v[208:211], v[34:37]
	v_mfma_f32_16x16x32_bf16 v[26:29], v[172:175], v[208:211], v[26:29]
	v_mfma_f32_16x16x32_bf16 v[18:21], v[164:167], v[216:219], v[18:21]
	v_mfma_f32_16x16x32_bf16 v[10:13], v[172:175], v[216:219], v[10:13]
	v_mfma_f32_16x16x32_bf16 v[6:9], v[164:167], v[224:227], v[6:9]
	v_mfma_f32_16x16x32_bf16 v[2:5], v[172:175], v[224:227], v[2:5]
	v_mfma_f32_16x16x32_bf16 v[50:53], v[168:171], v[186:189], v[50:53]
	v_mfma_f32_16x16x32_bf16 v[42:45], v[176:179], v[186:189], v[42:45]
	v_mfma_f32_16x16x32_bf16 v[34:37], v[168:171], v[212:215], v[34:37]
	v_mfma_f32_16x16x32_bf16 v[26:29], v[176:179], v[212:215], v[26:29]
	v_mfma_f32_16x16x32_bf16 v[18:21], v[168:171], v[220:223], v[18:21]
	v_mfma_f32_16x16x32_bf16 v[10:13], v[176:179], v[220:223], v[10:13]
	v_mfma_f32_16x16x32_bf16 v[6:9], v[168:171], v[228:231], v[6:9]
	v_mfma_f32_16x16x32_bf16 v[2:5], v[176:179], v[228:231], v[2:5]
	s_setprio 0
	s_barrier
	s_cbranch_vccz .Lgemm_head
	s_branch .LBB0_360
.Lgemm_head:
	ds_read_b128 v[148:151], v242
	ds_read_b128 v[152:155], v242 offset:1024
	ds_read_b128 v[156:159], v242 offset:2048
	ds_read_b128 v[160:163], v242 offset:3072
	ds_read_b128 v[164:167], v242 offset:16384
	ds_read_b128 v[168:171], v242 offset:17408
	ds_read_b128 v[172:175], v242 offset:18432
	ds_read_b128 v[176:179], v242 offset:19456
	v_lshl_add_u64 v[232:233], v[140:141], 0, s[50:51]
	s_add_i32 m0, s98, 0xc000
	ds_read_b128 v[182:185], v147
	ds_read_b128 v[186:189], v147 offset:1024
	ds_read_b128 v[208:211], v147 offset:2048
	ds_read_b128 v[212:215], v147 offset:3072
	ds_read_b128 v[216:219], v147 offset:4096
	ds_read_b128 v[220:223], v147 offset:5120
	ds_read_b128 v[224:227], v147 offset:6144
	ds_read_b128 v[228:231], v147 offset:7168
	global_load_lds_dwordx4 v[232:233], off
	v_lshl_add_u64 v[232:233], v[142:143], 0, s[50:51]
	s_add_i32 m0, s98, 0xe000
	s_nop 0
	global_load_lds_dwordx4 v[232:233], off
	s_waitcnt vmcnt(8)
	s_waitcnt lgkmcnt(0)
	s_barrier
	s_setprio 1
	v_mfma_f32_16x16x32_bf16 v[126:129], v[148:151], v[182:185], v[126:129]
	v_mfma_f32_16x16x32_bf16 v[122:125], v[156:159], v[182:185], v[122:125]
	v_mfma_f32_16x16x32_bf16 v[118:121], v[148:151], v[208:211], v[118:121]
	v_mfma_f32_16x16x32_bf16 v[110:113], v[156:159], v[208:211], v[110:113]
	v_mfma_f32_16x16x32_bf16 v[102:105], v[148:151], v[216:219], v[102:105]
	v_mfma_f32_16x16x32_bf16 v[94:97], v[156:159], v[216:219], v[94:97]
	v_mfma_f32_16x16x32_bf16 v[86:89], v[148:151], v[224:227], v[86:89]
	v_mfma_f32_16x16x32_bf16 v[78:81], v[156:159], v[224:227], v[78:81]
	v_mfma_f32_16x16x32_bf16 v[126:129], v[152:155], v[186:189], v[126:129]
	v_mfma_f32_16x16x32_bf16 v[122:125], v[160:163], v[186:189], v[122:125]
	v_mfma_f32_16x16x32_bf16 v[118:121], v[152:155], v[212:215], v[118:121]
	v_mfma_f32_16x16x32_bf16 v[110:113], v[160:163], v[212:215], v[110:113]
	v_mfma_f32_16x16x32_bf16 v[102:105], v[152:155], v[220:223], v[102:105]
	v_mfma_f32_16x16x32_bf16 v[94:97], v[160:163], v[220:223], v[94:97]
	v_mfma_f32_16x16x32_bf16 v[86:89], v[152:155], v[228:231], v[86:89]
	v_mfma_f32_16x16x32_bf16 v[78:81], v[160:163], v[228:231], v[78:81]
	v_mfma_f32_16x16x32_bf16 v[114:117], v[164:167], v[182:185], v[114:117]
	v_mfma_f32_16x16x32_bf16 v[106:109], v[172:175], v[182:185], v[106:109]
	v_mfma_f32_16x16x32_bf16 v[98:101], v[164:167], v[208:211], v[98:101]
	v_mfma_f32_16x16x32_bf16 v[90:93], v[172:175], v[208:211], v[90:93]
	v_mfma_f32_16x16x32_bf16 v[82:85], v[164:167], v[216:219], v[82:85]
	v_mfma_f32_16x16x32_bf16 v[74:77], v[172:175], v[216:219], v[74:77]
	v_mfma_f32_16x16x32_bf16 v[70:73], v[164:167], v[224:227], v[70:73]
	v_mfma_f32_16x16x32_bf16 v[66:69], v[172:175], v[224:227], v[66:69]
	v_mfma_f32_16x16x32_bf16 v[114:117], v[168:171], v[186:189], v[114:117]
	v_mfma_f32_16x16x32_bf16 v[106:109], v[176:179], v[186:189], v[106:109]
	v_mfma_f32_16x16x32_bf16 v[98:101], v[168:171], v[212:215], v[98:101]
	v_mfma_f32_16x16x32_bf16 v[90:93], v[176:179], v[212:215], v[90:93]
	v_mfma_f32_16x16x32_bf16 v[82:85], v[168:171], v[220:223], v[82:85]
	v_mfma_f32_16x16x32_bf16 v[74:77], v[176:179], v[220:223], v[74:77]
	v_mfma_f32_16x16x32_bf16 v[70:73], v[168:171], v[228:231], v[70:73]
	v_mfma_f32_16x16x32_bf16 v[66:69], v[176:179], v[228:231], v[66:69]
	s_setprio 0
	s_barrier
; #define PG8_STAGE(bufoff, gbase, voff) do { _Pragma("unroll") for (int _i = 0; _i < 2; ++_i) \
;         __builtin_amdgcn_global_load_lds((const unsigned*)((const char*)(gbase) + (voff)[_i]), (PG8_LAS unsigned*)(lds + (bufoff) + ldsw + _i * 8192), 16, 0, 0); } while (0)
; #define PG8_LDA(dst, b, h) do { _Pragma("unroll") for (int m = 0; m < 4; ++m) _Pragma("unroll") for (int k = 0; k < 2; ++k) dst[m][k] = *(const PG8_LAS bf16x8*)(lds + PG8_SA(b, h) + aoff + m * 2048 + k * 1024); } while (0)
; #define PG8_LDB(dst, b, h) do { _Pragma("unroll") for (int n = 0; n < 2; ++n) _Pragma("unroll") for (int k = 0; k < 2; ++k) dst[n][k] = *(const PG8_LAS bf16x8*)(lds + PG8_SB(b, h) + boff + n * 2048 + k * 1024); } while (0)
; #define PG8_MMA(ai, bj, At, Bt) do { __builtin_amdgcn_s_setprio(1); _Pragma("unroll") for (int m = 0; m < 4; ++m) _Pragma("unroll") for (int n = 0; n < 2; ++n) _Pragma("unroll") for (int k = 0; k < 2; ++k) \
;         acc[ai][bj][m][n] = __builtin_amdgcn_mfma_f32_16x16x32_bf16(Bt[n][k], At[m][k], acc[ai][bj][m][n], 0, 0, 0); __builtin_amdgcn_s_setprio(0); } while (0)
; #define PG8_WAIT_V(n) asm volatile("s_waitcnt vmcnt(" #n ")" ::: "memory")
; #define PG8_WAIT_L(n) asm volatile("s_waitcnt lgkmcnt(" #n ")" ::: "memory")
; #define PG8_BAR __builtin_amdgcn_s_barrier()
; #define PG8_SCHED __builtin_amdgcn_sched_barrier(0)
; template <class Epi, class Sched, bool ALIGN_EPI = false, bool SP2 = false>
; __device__ __forceinline__ void gemm_phase(PG8_LAS unsigned char* lds, const Gemm g, const Sched& S, const Epi& E) {
;     ...
;             PG8_LDA(At, 0, 1); PG8_STAGE(PG8_SB(0, 0), b2, voffB); PG8_STAGE(PG8_SB(0, 1), b2 + hstep, voffB); PG8_STAGE(PG8_SA(0, 0), a2, voffA);
;             PG8_WAIT_V(8); PG8_WAIT_L(0); PG8_BAR; PG8_MMA(1, 0, At, B0); PG8_MMA(1, 1, At, B1); PG8_BAR; PG8_SCHED;
;             PG8_LDB(B0, 1, 0); PG8_LDB(B1, 1, 1); PG8_SCHED; PG8_LDA(At, 1, 0); PG8_STAGE(PG8_SA(0, 1), a2 + hstep, voffA);
	s_add_i32 m0, s97, 0x10000
	ds_read_b128 v[182:185], v147 offset:16384
	ds_read_b128 v[186:189], v147 offset:17408
	ds_read_b128 v[208:211], v147 offset:18432
	ds_read_b128 v[212:215], v147 offset:19456
	ds_read_b128 v[216:219], v147 offset:20480
	ds_read_b128 v[220:223], v147 offset:21504
	ds_read_b128 v[224:227], v147 offset:22528
	ds_read_b128 v[228:231], v147 offset:23552
	global_load_lds_dwordx4 v0, s[56:57]
	s_add_i32 m0, s97, 0x12000
	s_add_u32 s38, s56, s16
	s_addc_u32 s39, s57, 0
	global_load_lds_dwordx4 v134, s[56:57]
	s_add_i32 m0, s97, 0x14000
	s_nop 0
	global_load_lds_dwordx4 v0, s[38:39]
	s_add_i32 m0, s97, 0x16000
	s_nop 0
	global_load_lds_dwordx4 v134, s[38:39]
	s_mov_b32 m0, s98
	s_nop 0
	global_load_lds_dwordx4 v130, s[62:63]
	s_mov_b32 m0, s99
	s_nop 0
	global_load_lds_dwordx4 v132, s[62:63]
	s_waitcnt vmcnt(8)
	s_waitcnt lgkmcnt(0)
	s_barrier
	s_setprio 1
	v_mfma_f32_16x16x32_bf16 v[62:65], v[148:151], v[182:185], v[62:65]
	v_mfma_f32_16x16x32_bf16 v[58:61], v[156:159], v[182:185], v[58:61]
	v_mfma_f32_16x16x32_bf16 v[54:57], v[148:151], v[208:211], v[54:57]
	v_mfma_f32_16x16x32_bf16 v[46:49], v[156:159], v[208:211], v[46:49]
	v_mfma_f32_16x16x32_bf16 v[38:41], v[148:151], v[216:219], v[38:41]
	v_mfma_f32_16x16x32_bf16 v[30:33], v[156:159], v[216:219], v[30:33]
	v_mfma_f32_16x16x32_bf16 v[22:25], v[148:151], v[224:227], v[22:25]
	v_mfma_f32_16x16x32_bf16 v[14:17], v[156:159], v[224:227], v[14:17]
	v_mfma_f32_16x16x32_bf16 v[62:65], v[152:155], v[186:189], v[62:65]
	v_mfma_f32_16x16x32_bf16 v[58:61], v[160:163], v[186:189], v[58:61]
	v_mfma_f32_16x16x32_bf16 v[54:57], v[152:155], v[212:215], v[54:57]
	v_mfma_f32_16x16x32_bf16 v[46:49], v[160:163], v[212:215], v[46:49]
	v_mfma_f32_16x16x32_bf16 v[38:41], v[152:155], v[220:223], v[38:41]
	v_mfma_f32_16x16x32_bf16 v[30:33], v[160:163], v[220:223], v[30:33]
	v_mfma_f32_16x16x32_bf16 v[22:25], v[152:155], v[228:231], v[22:25]
	v_mfma_f32_16x16x32_bf16 v[14:17], v[160:163], v[228:231], v[14:17]
	v_mfma_f32_16x16x32_bf16 v[50:53], v[164:167], v[182:185], v[50:53]
	v_mfma_f32_16x16x32_bf16 v[42:45], v[172:175], v[182:185], v[42:45]
	v_mfma_f32_16x16x32_bf16 v[34:37], v[164:167], v[208:211], v[34:37]
	v_mfma_f32_16x16x32_bf16 v[26:29], v[172:175], v[208:211], v[26:29]
	v_mfma_f32_16x16x32_bf16 v[18:21], v[164:167], v[216:219], v[18:21]
	v_mfma_f32_16x16x32_bf16 v[10:13], v[172:175], v[216:219], v[10:13]
	v_mfma_f32_16x16x32_bf16 v[6:9], v[164:167], v[224:227], v[6:9]
	v_mfma_f32_16x16x32_bf16 v[2:5], v[172:175], v[224:227], v[2:5]
	v_mfma_f32_16x16x32_bf16 v[50:53], v[168:171], v[186:189], v[50:53]
	v_mfma_f32_16x16x32_bf16 v[42:45], v[176:179], v[186:189], v[42:45]
	v_mfma_f32_16x16x32_bf16 v[34:37], v[168:171], v[212:215], v[34:37]
	v_mfma_f32_16x16x32_bf16 v[26:29], v[176:179], v[212:215], v[26:29]
	v_mfma_f32_16x16x32_bf16 v[18:21], v[168:171], v[220:223], v[18:21]
	v_mfma_f32_16x16x32_bf16 v[10:13], v[176:179], v[220:223], v[10:13]
	v_mfma_f32_16x16x32_bf16 v[6:9], v[168:171], v[228:231], v[6:9]
	v_mfma_f32_16x16x32_bf16 v[2:5], v[176:179], v[228:231], v[2:5]
	s_setprio 0
	s_barrier
	ds_read_b128 v[148:151], v242 offset:32768
	ds_read_b128 v[152:155], v242 offset:33792
	ds_read_b128 v[156:159], v242 offset:34816
	ds_read_b128 v[160:163], v242 offset:35840
	ds_read_b128 v[164:167], v242 offset:49152
	ds_read_b128 v[168:171], v242 offset:50176
	ds_read_b128 v[172:175], v242 offset:51200
	ds_read_b128 v[176:179], v242 offset:52224
	s_add_u32 s38, s62, s16
	s_addc_u32 s39, s63, 0
	s_mov_b32 m0, s68
	ds_read_b128 v[182:185], v147 offset:32768
	ds_read_b128 v[186:189], v147 offset:33792
	ds_read_b128 v[208:211], v147 offset:34816
	ds_read_b128 v[212:215], v147 offset:35840
	ds_read_b128 v[216:219], v147 offset:36864
	ds_read_b128 v[220:223], v147 offset:37888
	ds_read_b128 v[224:227], v147 offset:38912
	ds_read_b128 v[228:231], v147 offset:39936
	global_load_lds_dwordx4 v130, s[38:39]
	s_mov_b32 m0, s64
	s_nop 0
	global_load_lds_dwordx4 v132, s[38:39]
	s_waitcnt vmcnt(8)
	s_waitcnt lgkmcnt(0)
	s_barrier
; #define PG8_STAGE(bufoff, gbase, voff) do { _Pragma("unroll") for (int _i = 0; _i < 2; ++_i) \
;         __builtin_amdgcn_global_load_lds((const unsigned*)((const char*)(gbase) + (voff)[_i]), (PG8_LAS unsigned*)(lds + (bufoff) + ldsw + _i * 8192), 16, 0, 0); } while (0)
; #define PG8_LDA(dst, b, h) do { _Pragma("unroll") for (int m = 0; m < 4; ++m) _Pragma("unroll") for (int k = 0; k < 2; ++k) dst[m][k] = *(const PG8_LAS bf16x8*)(lds + PG8_SA(b, h) + aoff + m * 2048 + k * 1024); } while (0)
; #define PG8_MMA(ai, bj, At, Bt) do { __builtin_amdgcn_s_setprio(1); _Pragma("unroll") for (int m = 0; m < 4; ++m) _Pragma("unroll") for (int n = 0; n < 2; ++n) _Pragma("unroll") for (int k = 0; k < 2; ++k) \
;         acc[ai][bj][m][n] = __builtin_amdgcn_mfma_f32_16x16x32_bf16(Bt[n][k], At[m][k], acc[ai][bj][m][n], 0, 0, 0); __builtin_amdgcn_s_setprio(0); } while (0)
; #define PG8_WAIT_V(n) asm volatile("s_waitcnt vmcnt(" #n ")" ::: "memory")
; #define PG8_WAIT_L(n) asm volatile("s_waitcnt lgkmcnt(" #n ")" ::: "memory")
; #define PG8_BAR __builtin_amdgcn_s_barrier()
; #define PG8_SCHED __builtin_amdgcn_sched_barrier(0)
; template <class Epi, class Sched, bool ALIGN_EPI = false, bool SP2 = false>
; __device__ __forceinline__ void gemm_phase(PG8_LAS unsigned char* lds, const Gemm g, const Sched& S, const Epi& E) {
;     ...
;             PG8_WAIT_V(8); PG8_WAIT_L(0); PG8_BAR; PG8_MMA(0, 0, At, B0); PG8_MMA(0, 1, At, B1); PG8_BAR; PG8_SCHED;
;             PG8_LDA(At, 1, 1); PG8_STAGE(PG8_SB(1, 0), b3, voffB); PG8_STAGE(PG8_SB(1, 1), b3 + hstep, voffB); PG8_STAGE(PG8_SA(1, 0), a3, voffA);
;             PG8_WAIT_V(8); PG8_WAIT_L(0); PG8_BAR; PG8_MMA(1, 0, At, B0); PG8_MMA(1, 1, At, B1); PG8_BAR; PG8_SCHED;
	s_setprio 1
	v_mfma_f32_16x16x32_bf16 v[126:129], v[148:151], v[182:185], v[126:129]
	v_mfma_f32_16x16x32_bf16 v[122:125], v[156:159], v[182:185], v[122:125]
	v_mfma_f32_16x16x32_bf16 v[118:121], v[148:151], v[208:211], v[118:121]
	v_mfma_f32_16x16x32_bf16 v[110:113], v[156:159], v[208:211], v[110:113]
	v_mfma_f32_16x16x32_bf16 v[102:105], v[148:151], v[216:219], v[102:105]
	v_mfma_f32_16x16x32_bf16 v[94:97], v[156:159], v[216:219], v[94:97]
	v_mfma_f32_16x16x32_bf16 v[86:89], v[148:151], v[224:227], v[86:89]
	v_mfma_f32_16x16x32_bf16 v[78:81], v[156:159], v[224:227], v[78:81]
	v_mfma_f32_16x16x32_bf16 v[126:129], v[152:155], v[186:189], v[126:129]
	v_mfma_f32_16x16x32_bf16 v[122:125], v[160:163], v[186:189], v[122:125]
	v_mfma_f32_16x16x32_bf16 v[118:121], v[152:155], v[212:215], v[118:121]
	v_mfma_f32_16x16x32_bf16 v[110:113], v[160:163], v[212:215], v[110:113]
	v_mfma_f32_16x16x32_bf16 v[102:105], v[152:155], v[220:223], v[102:105]
	v_mfma_f32_16x16x32_bf16 v[94:97], v[160:163], v[220:223], v[94:97]
	v_mfma_f32_16x16x32_bf16 v[86:89], v[152:155], v[228:231], v[86:89]
	v_mfma_f32_16x16x32_bf16 v[78:81], v[160:163], v[228:231], v[78:81]
	v_mfma_f32_16x16x32_bf16 v[114:117], v[164:167], v[182:185], v[114:117]
	v_mfma_f32_16x16x32_bf16 v[106:109], v[172:175], v[182:185], v[106:109]
	v_mfma_f32_16x16x32_bf16 v[98:101], v[164:167], v[208:211], v[98:101]
	v_mfma_f32_16x16x32_bf16 v[90:93], v[172:175], v[208:211], v[90:93]
	v_mfma_f32_16x16x32_bf16 v[82:85], v[164:167], v[216:219], v[82:85]
	v_mfma_f32_16x16x32_bf16 v[74:77], v[172:175], v[216:219], v[74:77]
	v_mfma_f32_16x16x32_bf16 v[70:73], v[164:167], v[224:227], v[70:73]
	v_mfma_f32_16x16x32_bf16 v[66:69], v[172:175], v[224:227], v[66:69]
	v_mfma_f32_16x16x32_bf16 v[114:117], v[168:171], v[186:189], v[114:117]
	v_mfma_f32_16x16x32_bf16 v[106:109], v[176:179], v[186:189], v[106:109]
	v_mfma_f32_16x16x32_bf16 v[98:101], v[168:171], v[212:215], v[98:101]
	v_mfma_f32_16x16x32_bf16 v[90:93], v[176:179], v[212:215], v[90:93]
	v_mfma_f32_16x16x32_bf16 v[82:85], v[168:171], v[220:223], v[82:85]
	v_mfma_f32_16x16x32_bf16 v[74:77], v[176:179], v[220:223], v[74:77]
	v_mfma_f32_16x16x32_bf16 v[70:73], v[168:171], v[228:231], v[70:73]
	v_mfma_f32_16x16x32_bf16 v[66:69], v[176:179], v[228:231], v[66:69]
	s_setprio 0
	s_barrier
	s_add_u32 s38, s56, s60
	s_addc_u32 s39, s57, s61
	s_add_i32 m0, s97, 0x18000
	ds_read_b128 v[182:185], v147 offset:49152
	ds_read_b128 v[186:189], v147 offset:50176
	ds_read_b128 v[208:211], v147 offset:51200
	ds_read_b128 v[212:215], v147 offset:52224
	ds_read_b128 v[216:219], v147 offset:53248
	ds_read_b128 v[220:223], v147 offset:54272
	ds_read_b128 v[224:227], v147 offset:55296
	ds_read_b128 v[228:231], v147 offset:56320
	global_load_lds_dwordx4 v0, s[38:39]
	s_add_i32 m0, s97, 0x1a000
	s_nop 0
	global_load_lds_dwordx4 v134, s[38:39]
	s_add_u32 s38, s38, s16
	s_addc_u32 s39, s39, 0
	s_add_i32 m0, s97, 0x1c000
	global_load_lds_dwordx4 v0, s[38:39]
	s_add_i32 m0, s97, 0x1e000
	s_nop 0
	global_load_lds_dwordx4 v134, s[38:39]
	s_mov_b32 m0, s72
	s_nop 0
	global_load_lds_dwordx4 v130, s[82:83]
	s_mov_b32 m0, s73
	s_nop 0
	global_load_lds_dwordx4 v132, s[82:83]
	s_add_u32 s50, s50, s48
	s_addc_u32 s51, s51, s49
	s_cmp_ge_u32 s80, s13
	s_cselect_b64 vcc, -1, 0
	s_cbranch_scc1 .Lgemm_ctl_done
	s_cmp_eq_u32 s88, s80
	s_cbranch_scc1 .Lgemm_ctl_last
	s_add_u32 s62, s18, s50
	s_addc_u32 s63, s19, s51
	s_add_u32 s56, s87, s50
	s_addc_u32 s57, s33, s51
	s_mov_b64 s[60:61], s[44:45]
	s_branch .Lgemm_ctl_join
